# all GEMM epilogues with batched loads (EpiUp, EpiRes bf16, EpiPle) plus contiguous-store final norm, on top of previous best
# baseline (speedup 1.0000x reference)
; __device__ __forceinline__ u32x4 pack8(f32x4 a, f32x4 b) { u32x4 w; w.x = cvt_pk(a[0], a[1]); w.y = cvt_pk(a[2], a[3]); w.z = cvt_pk(b[0], b[1]); w.w = cvt_pk(b[2], b[3]); return w; }
; __device__ __forceinline__ float row_rstd(const float* ss, int row) {
;     const f32x4* p = (const f32x4*)(ss + (size_t)row * 16); const f32x4 a = p[0], b = p[1], c = p[2], d = p[3];
;     const float s = (((a[0] + a[1]) + (a[2] + a[3])) + ((b[0] + b[1]) + (b[2] + b[3]))) + (((c[0] + c[1]) + (c[2] + c[3])) + ((d[0] + d[1]) + (d[2] + d[3])));
;     return __builtin_amdgcn_rsqf(s * (1.f / DM) + EPS);
; }
;     __device__ __forceinline__ void operator()(EPI_ARGS) const {
;         const int row0 = u.pm * 256 + wr * 64 + fr, colt = u.pn * 256 + wc * 32 + 8 * fq;
; #pragma unroll
;         for (int ai = 0; ai < 2; ++ai)
; #pragma unroll
;             for (int m = 0; m < 4; ++m) { const int row = row0 + ai * 128 + m * 16; const float rs = row_rstd(ss, row); bf16_t* rowp = H + (size_t)row * FF + colt;
; #pragma unroll
;                 for (int bj = 0; bj < 2; ++bj) { f32x4 v0 = acc[ai][bj][m][0] * rs, v1 = acc[ai][bj][m][1] * rs;
; #pragma unroll
;                     for (int e = 0; e < 4; ++e) { const float a = fmaxf(v0[e], 0.f), b = fmaxf(v1[e], 0.f); v0[e] = a * a; v1[e] = b * b; }
;                     *(u32x4*)(rowp + bj * 128) = pack8(v0, v1); } }
.LBB0_886:
	s_lshl_b32 s13, s20, 8
	s_add_i32 s13, s13, s40
	v_readlane_b32 s22, v247, 37
	v_readlane_b32 s23, v247, 38
	v_and_or_b32 v142, v144, 15, s13
	v_mov_b32_e32 v143, 0
	v_lshlrev_b64 v[140:141], 6, v[142:143]
	v_lshl_add_u64 v[140:141], s[2:3], 0, v[140:141]
	global_load_dwordx4 v[150:153], v[140:141], off
	global_load_dwordx4 v[154:157], v[140:141], off offset:16
	global_load_dwordx4 v[158:161], v[140:141], off offset:32
	global_load_dwordx4 v[162:165], v[140:141], off offset:48
	global_load_dwordx4 v[166:169], v[140:141], off offset:1024
	global_load_dwordx4 v[170:173], v[140:141], off offset:1040
	global_load_dwordx4 v[174:177], v[140:141], off offset:1056
	global_load_dwordx4 v[178:181], v[140:141], off offset:1072
	global_load_dwordx4 v[186:189], v[140:141], off offset:2048
	global_load_dwordx4 v[190:193], v[140:141], off offset:2064
	global_load_dwordx4 v[194:197], v[140:141], off offset:2080
	global_load_dwordx4 v[198:201], v[140:141], off offset:2096
	global_load_dwordx4 v[202:205], v[140:141], off offset:3072
	global_load_dwordx4 v[206:209], v[140:141], off offset:3088
	global_load_dwordx4 v[210:213], v[140:141], off offset:3104
	global_load_dwordx4 v[238:241], v[140:141], off offset:3120
	s_lshl_b32 s13, s47, 8
	s_or_b32 s13, s13, s41
	v_ashrrev_i32_e32 v246, 1, v144
	v_and_b32_e32 v246, -8, v246
	v_add_u32_e32 v246, s13, v246
	v_lshlrev_b32_e32 v246, 1, v246
	v_lshl_add_u32 v246, v142, 13, v246
	v_add_u32_e32 v142, 0x80, v142
	v_lshlrev_b64 v[140:141], 6, v[142:143]
	v_lshl_add_u64 v[140:141], s[2:3], 0, v[140:141]
	s_waitcnt vmcnt(0)
	v_add_f32_e32 v150, v150, v151
	v_add_f32_e32 v152, v152, v153
	v_add_f32_e32 v154, v154, v155
	v_add_f32_e32 v156, v156, v157
	v_add_f32_e32 v158, v158, v159
	v_add_f32_e32 v160, v160, v161
	v_add_f32_e32 v162, v162, v163
	v_add_f32_e32 v164, v164, v165
	v_add_f32_e32 v150, v150, v152
	v_add_f32_e32 v154, v154, v156
	v_add_f32_e32 v158, v158, v160
	v_add_f32_e32 v162, v162, v164
	v_add_f32_e32 v150, v150, v154
	v_add_f32_e32 v158, v158, v162
	v_add_f32_e32 v150, v150, v158
	v_fmamk_f32 v150, v150, 0x3a800000, v149
	v_rsq_f32_e32 v222, v150
	v_add_f32_e32 v166, v166, v167
	v_add_f32_e32 v168, v168, v169
	v_add_f32_e32 v170, v170, v171
	v_add_f32_e32 v172, v172, v173
	v_add_f32_e32 v174, v174, v175
	v_add_f32_e32 v176, v176, v177
	v_add_f32_e32 v178, v178, v179
	v_add_f32_e32 v180, v180, v181
	v_add_f32_e32 v166, v166, v168
	v_add_f32_e32 v170, v170, v172
	v_add_f32_e32 v174, v174, v176
	v_add_f32_e32 v178, v178, v180
	v_add_f32_e32 v166, v166, v170
	v_add_f32_e32 v174, v174, v178
	v_add_f32_e32 v166, v166, v174
	v_fmamk_f32 v166, v166, 0x3a800000, v149
	v_rsq_f32_e32 v224, v166
	v_add_f32_e32 v186, v186, v187
	v_add_f32_e32 v188, v188, v189
	v_add_f32_e32 v190, v190, v191
	v_add_f32_e32 v192, v192, v193
	v_add_f32_e32 v194, v194, v195
	v_add_f32_e32 v196, v196, v197
	v_add_f32_e32 v198, v198, v199
	v_add_f32_e32 v200, v200, v201
	v_add_f32_e32 v186, v186, v188
	v_add_f32_e32 v190, v190, v192
	v_add_f32_e32 v194, v194, v196
	v_add_f32_e32 v198, v198, v200
	v_add_f32_e32 v186, v186, v190
	v_add_f32_e32 v194, v194, v198
	v_add_f32_e32 v186, v186, v194
	v_fmamk_f32 v186, v186, 0x3a800000, v149
	v_rsq_f32_e32 v226, v186
	v_add_f32_e32 v202, v202, v203
	v_add_f32_e32 v204, v204, v205
	v_add_f32_e32 v206, v206, v207
	v_add_f32_e32 v208, v208, v209
	v_add_f32_e32 v210, v210, v211
	v_add_f32_e32 v212, v212, v213
	v_add_f32_e32 v238, v238, v239
	v_add_f32_e32 v240, v240, v241
	v_add_f32_e32 v202, v202, v204
	v_add_f32_e32 v206, v206, v208
	v_add_f32_e32 v210, v210, v212
	v_add_f32_e32 v238, v238, v240
	v_add_f32_e32 v202, v202, v206
	v_add_f32_e32 v210, v210, v238
	v_add_f32_e32 v202, v202, v210
	v_fmamk_f32 v202, v202, 0x3a800000, v149
	v_rsq_f32_e32 v228, v202
	global_load_dwordx4 v[150:153], v[140:141], off
	global_load_dwordx4 v[154:157], v[140:141], off offset:16
	global_load_dwordx4 v[158:161], v[140:141], off offset:32
	global_load_dwordx4 v[162:165], v[140:141], off offset:48
	global_load_dwordx4 v[166:169], v[140:141], off offset:1024
	global_load_dwordx4 v[170:173], v[140:141], off offset:1040
	global_load_dwordx4 v[174:177], v[140:141], off offset:1056
	global_load_dwordx4 v[178:181], v[140:141], off offset:1072
	global_load_dwordx4 v[186:189], v[140:141], off offset:2048
	global_load_dwordx4 v[190:193], v[140:141], off offset:2064
	global_load_dwordx4 v[194:197], v[140:141], off offset:2080
	global_load_dwordx4 v[198:201], v[140:141], off offset:2096
	global_load_dwordx4 v[202:205], v[140:141], off offset:3072
	global_load_dwordx4 v[206:209], v[140:141], off offset:3088
	global_load_dwordx4 v[210:213], v[140:141], off offset:3104
	global_load_dwordx4 v[238:241], v[140:141], off offset:3120
	v_pk_mul_f32 v[112:113], v[112:113], v[222:223] op_sel_hi:[1,0]
	v_pk_mul_f32 v[114:115], v[114:115], v[222:223] op_sel_hi:[1,0]
	v_pk_mul_f32 v[116:117], v[116:117], v[222:223] op_sel_hi:[1,0]
	v_pk_mul_f32 v[118:119], v[118:119], v[222:223] op_sel_hi:[1,0]
	v_pk_mul_f32 v[120:121], v[120:121], v[222:223] op_sel_hi:[1,0]
	v_pk_mul_f32 v[122:123], v[122:123], v[222:223] op_sel_hi:[1,0]
	v_pk_mul_f32 v[124:125], v[124:125], v[222:223] op_sel_hi:[1,0]
	v_pk_mul_f32 v[126:127], v[126:127], v[222:223] op_sel_hi:[1,0]
	v_max_f32_e32 v112, 0, v112
	v_max_f32_e32 v113, 0, v113
	v_max_f32_e32 v114, 0, v114
	v_max_f32_e32 v115, 0, v115
	v_max_f32_e32 v116, 0, v116
	v_max_f32_e32 v117, 0, v117
	v_max_f32_e32 v118, 0, v118
	v_max_f32_e32 v119, 0, v119
	v_max_f32_e32 v120, 0, v120
	v_max_f32_e32 v121, 0, v121
	v_max_f32_e32 v122, 0, v122
	v_max_f32_e32 v123, 0, v123
	v_max_f32_e32 v124, 0, v124
; __device__ __forceinline__ u32x4 pack8(f32x4 a, f32x4 b) { u32x4 w; w.x = cvt_pk(a[0], a[1]); w.y = cvt_pk(a[2], a[3]); w.z = cvt_pk(b[0], b[1]); w.w = cvt_pk(b[2], b[3]); return w; }
;     __device__ __forceinline__ void operator()(EPI_ARGS) const {
;     ...
;             for (int m = 0; m < 4; ++m) { const int row = row0 + ai * 128 + m * 16; const float rs = row_rstd(ss, row); bf16_t* rowp = H + (size_t)row * FF + colt;
; #pragma unroll
;                 for (int bj = 0; bj < 2; ++bj) { f32x4 v0 = acc[ai][bj][m][0] * rs, v1 = acc[ai][bj][m][1] * rs;
; #pragma unroll
;                     for (int e = 0; e < 4; ++e) { const float a = fmaxf(v0[e], 0.f), b = fmaxf(v1[e], 0.f); v0[e] = a * a; v1[e] = b * b; }
;                     *(u32x4*)(rowp + bj * 128) = pack8(v0, v1); } }
	v_max_f32_e32 v125, 0, v125
	v_max_f32_e32 v126, 0, v126
	v_max_f32_e32 v127, 0, v127
	v_pk_mul_f32 v[112:113], v[112:113], v[112:113]
	v_pk_mul_f32 v[114:115], v[114:115], v[114:115]
	v_pk_mul_f32 v[116:117], v[116:117], v[116:117]
	v_pk_mul_f32 v[118:119], v[118:119], v[118:119]
	v_pk_mul_f32 v[120:121], v[120:121], v[120:121]
	v_pk_mul_f32 v[122:123], v[122:123], v[122:123]
	v_pk_mul_f32 v[124:125], v[124:125], v[124:125]
	v_pk_mul_f32 v[126:127], v[126:127], v[126:127]
	v_cvt_pk_bf16_f32 v230, v124, v125
	v_cvt_pk_bf16_f32 v231, v126, v127
	v_cvt_pk_bf16_f32 v232, v120, v121
	v_cvt_pk_bf16_f32 v233, v122, v123
	v_cvt_pk_bf16_f32 v234, v116, v117
	v_cvt_pk_bf16_f32 v235, v118, v119
	v_cvt_pk_bf16_f32 v236, v112, v113
	v_cvt_pk_bf16_f32 v237, v114, v115
	global_store_dwordx4 v246, v[230:233], s[22:23]
	global_store_dwordx4 v246, v[234:237], s[22:23] offset:256
	s_add_u32 s22, s22, 0x20000
	s_addc_u32 s23, s23, 0
	v_pk_mul_f32 v[96:97], v[96:97], v[224:225] op_sel_hi:[1,0]
	v_pk_mul_f32 v[98:99], v[98:99], v[224:225] op_sel_hi:[1,0]
	v_pk_mul_f32 v[100:101], v[100:101], v[224:225] op_sel_hi:[1,0]
	v_pk_mul_f32 v[102:103], v[102:103], v[224:225] op_sel_hi:[1,0]
	v_pk_mul_f32 v[104:105], v[104:105], v[224:225] op_sel_hi:[1,0]
	v_pk_mul_f32 v[106:107], v[106:107], v[224:225] op_sel_hi:[1,0]
	v_pk_mul_f32 v[108:109], v[108:109], v[224:225] op_sel_hi:[1,0]
	v_pk_mul_f32 v[110:111], v[110:111], v[224:225] op_sel_hi:[1,0]
	v_max_f32_e32 v96, 0, v96
	v_max_f32_e32 v97, 0, v97
	v_max_f32_e32 v98, 0, v98
	v_max_f32_e32 v99, 0, v99
	v_max_f32_e32 v100, 0, v100
	v_max_f32_e32 v101, 0, v101
	v_max_f32_e32 v102, 0, v102
	v_max_f32_e32 v103, 0, v103
	v_max_f32_e32 v104, 0, v104
	v_max_f32_e32 v105, 0, v105
	v_max_f32_e32 v106, 0, v106
	v_max_f32_e32 v107, 0, v107
	v_max_f32_e32 v108, 0, v108
	v_max_f32_e32 v109, 0, v109
	v_max_f32_e32 v110, 0, v110
	v_max_f32_e32 v111, 0, v111
	v_pk_mul_f32 v[96:97], v[96:97], v[96:97]
	v_pk_mul_f32 v[98:99], v[98:99], v[98:99]
	v_pk_mul_f32 v[100:101], v[100:101], v[100:101]
	v_pk_mul_f32 v[102:103], v[102:103], v[102:103]
	v_pk_mul_f32 v[104:105], v[104:105], v[104:105]
	v_pk_mul_f32 v[106:107], v[106:107], v[106:107]
	v_pk_mul_f32 v[108:109], v[108:109], v[108:109]
	v_pk_mul_f32 v[110:111], v[110:111], v[110:111]
	v_cvt_pk_bf16_f32 v230, v108, v109
	v_cvt_pk_bf16_f32 v231, v110, v111
	v_cvt_pk_bf16_f32 v232, v104, v105
	v_cvt_pk_bf16_f32 v233, v106, v107
	v_cvt_pk_bf16_f32 v234, v100, v101
	v_cvt_pk_bf16_f32 v235, v102, v103
	v_cvt_pk_bf16_f32 v236, v96, v97
	v_cvt_pk_bf16_f32 v237, v98, v99
	global_store_dwordx4 v246, v[230:233], s[22:23]
	global_store_dwordx4 v246, v[234:237], s[22:23] offset:256
	s_add_u32 s22, s22, 0x20000
	s_addc_u32 s23, s23, 0
	v_pk_mul_f32 v[80:81], v[80:81], v[226:227] op_sel_hi:[1,0]
	v_pk_mul_f32 v[82:83], v[82:83], v[226:227] op_sel_hi:[1,0]
	v_pk_mul_f32 v[84:85], v[84:85], v[226:227] op_sel_hi:[1,0]
	v_pk_mul_f32 v[86:87], v[86:87], v[226:227] op_sel_hi:[1,0]
	v_pk_mul_f32 v[88:89], v[88:89], v[226:227] op_sel_hi:[1,0]
	v_pk_mul_f32 v[90:91], v[90:91], v[226:227] op_sel_hi:[1,0]
	v_pk_mul_f32 v[92:93], v[92:93], v[226:227] op_sel_hi:[1,0]
	v_pk_mul_f32 v[94:95], v[94:95], v[226:227] op_sel_hi:[1,0]
	v_max_f32_e32 v80, 0, v80
	v_max_f32_e32 v81, 0, v81
	v_max_f32_e32 v82, 0, v82
	v_max_f32_e32 v83, 0, v83
	v_max_f32_e32 v84, 0, v84
	v_max_f32_e32 v85, 0, v85
	v_max_f32_e32 v86, 0, v86
	v_max_f32_e32 v87, 0, v87
	v_max_f32_e32 v88, 0, v88
	v_max_f32_e32 v89, 0, v89
	v_max_f32_e32 v90, 0, v90
	v_max_f32_e32 v91, 0, v91
	v_max_f32_e32 v92, 0, v92
	v_max_f32_e32 v93, 0, v93
	v_max_f32_e32 v94, 0, v94
	v_max_f32_e32 v95, 0, v95
	v_pk_mul_f32 v[80:81], v[80:81], v[80:81]
	v_pk_mul_f32 v[82:83], v[82:83], v[82:83]
	v_pk_mul_f32 v[84:85], v[84:85], v[84:85]
	v_pk_mul_f32 v[86:87], v[86:87], v[86:87]
	v_pk_mul_f32 v[88:89], v[88:89], v[88:89]
	v_pk_mul_f32 v[90:91], v[90:91], v[90:91]
	v_pk_mul_f32 v[92:93], v[92:93], v[92:93]
	v_pk_mul_f32 v[94:95], v[94:95], v[94:95]
	v_cvt_pk_bf16_f32 v230, v92, v93
	v_cvt_pk_bf16_f32 v231, v94, v95
	v_cvt_pk_bf16_f32 v232, v88, v89
	v_cvt_pk_bf16_f32 v233, v90, v91
	v_cvt_pk_bf16_f32 v234, v84, v85
	v_cvt_pk_bf16_f32 v235, v86, v87
	v_cvt_pk_bf16_f32 v236, v80, v81
	v_cvt_pk_bf16_f32 v237, v82, v83
	global_store_dwordx4 v246, v[230:233], s[22:23]
	global_store_dwordx4 v246, v[234:237], s[22:23] offset:256
	s_add_u32 s22, s22, 0x20000
	s_addc_u32 s23, s23, 0
	v_pk_mul_f32 v[64:65], v[64:65], v[228:229] op_sel_hi:[1,0]
	v_pk_mul_f32 v[66:67], v[66:67], v[228:229] op_sel_hi:[1,0]
	v_pk_mul_f32 v[68:69], v[68:69], v[228:229] op_sel_hi:[1,0]
	v_pk_mul_f32 v[70:71], v[70:71], v[228:229] op_sel_hi:[1,0]
	v_pk_mul_f32 v[72:73], v[72:73], v[228:229] op_sel_hi:[1,0]
	v_pk_mul_f32 v[74:75], v[74:75], v[228:229] op_sel_hi:[1,0]
	v_pk_mul_f32 v[76:77], v[76:77], v[228:229] op_sel_hi:[1,0]
	v_pk_mul_f32 v[78:79], v[78:79], v[228:229] op_sel_hi:[1,0]
	v_max_f32_e32 v64, 0, v64
	v_max_f32_e32 v65, 0, v65
	v_max_f32_e32 v66, 0, v66
	v_max_f32_e32 v67, 0, v67
	v_max_f32_e32 v68, 0, v68
	v_max_f32_e32 v69, 0, v69
	v_max_f32_e32 v70, 0, v70
	v_max_f32_e32 v71, 0, v71
	v_max_f32_e32 v72, 0, v72
	v_max_f32_e32 v73, 0, v73
	v_max_f32_e32 v74, 0, v74
	v_max_f32_e32 v75, 0, v75
	v_max_f32_e32 v76, 0, v76
	v_max_f32_e32 v77, 0, v77
	v_max_f32_e32 v78, 0, v78
	v_max_f32_e32 v79, 0, v79
	v_pk_mul_f32 v[64:65], v[64:65], v[64:65]
	v_pk_mul_f32 v[66:67], v[66:67], v[66:67]
	v_pk_mul_f32 v[68:69], v[68:69], v[68:69]
	v_pk_mul_f32 v[70:71], v[70:71], v[70:71]
	v_pk_mul_f32 v[72:73], v[72:73], v[72:73]
	v_pk_mul_f32 v[74:75], v[74:75], v[74:75]
	v_pk_mul_f32 v[76:77], v[76:77], v[76:77]
	v_pk_mul_f32 v[78:79], v[78:79], v[78:79]
	v_cvt_pk_bf16_f32 v230, v76, v77
	v_cvt_pk_bf16_f32 v231, v78, v79
	v_cvt_pk_bf16_f32 v232, v72, v73
	v_cvt_pk_bf16_f32 v233, v74, v75
	v_cvt_pk_bf16_f32 v234, v68, v69
	v_cvt_pk_bf16_f32 v235, v70, v71
	v_cvt_pk_bf16_f32 v236, v64, v65
	v_cvt_pk_bf16_f32 v237, v66, v67
	global_store_dwordx4 v246, v[230:233], s[22:23]
	global_store_dwordx4 v246, v[234:237], s[22:23] offset:256
	s_add_u32 s22, s22, 0xa0000
	s_addc_u32 s23, s23, 0
	s_waitcnt vmcnt(8)
; __device__ __forceinline__ u32x4 pack8(f32x4 a, f32x4 b) { u32x4 w; w.x = cvt_pk(a[0], a[1]); w.y = cvt_pk(a[2], a[3]); w.z = cvt_pk(b[0], b[1]); w.w = cvt_pk(b[2], b[3]); return w; }
; __device__ __forceinline__ float row_rstd(const float* ss, int row) {
;     const f32x4* p = (const f32x4*)(ss + (size_t)row * 16); const f32x4 a = p[0], b = p[1], c = p[2], d = p[3];
;     const float s = (((a[0] + a[1]) + (a[2] + a[3])) + ((b[0] + b[1]) + (b[2] + b[3]))) + (((c[0] + c[1]) + (c[2] + c[3])) + ((d[0] + d[1]) + (d[2] + d[3])));
;     return __builtin_amdgcn_rsqf(s * (1.f / DM) + EPS);
; }
;     __device__ __forceinline__ void operator()(EPI_ARGS) const {
;     ...
;             for (int m = 0; m < 4; ++m) { const int row = row0 + ai * 128 + m * 16; const float rs = row_rstd(ss, row); bf16_t* rowp = H + (size_t)row * FF + colt;
; #pragma unroll
;                 for (int bj = 0; bj < 2; ++bj) { f32x4 v0 = acc[ai][bj][m][0] * rs, v1 = acc[ai][bj][m][1] * rs;
; #pragma unroll
;                     for (int e = 0; e < 4; ++e) { const float a = fmaxf(v0[e], 0.f), b = fmaxf(v1[e], 0.f); v0[e] = a * a; v1[e] = b * b; }
;                     *(u32x4*)(rowp + bj * 128) = pack8(v0, v1); } }
	v_add_f32_e32 v150, v150, v151
	v_add_f32_e32 v152, v152, v153
	v_add_f32_e32 v154, v154, v155
	v_add_f32_e32 v156, v156, v157
	v_add_f32_e32 v158, v158, v159
	v_add_f32_e32 v160, v160, v161
	v_add_f32_e32 v162, v162, v163
	v_add_f32_e32 v164, v164, v165
	v_add_f32_e32 v150, v150, v152
	v_add_f32_e32 v154, v154, v156
	v_add_f32_e32 v158, v158, v160
	v_add_f32_e32 v162, v162, v164
	v_add_f32_e32 v150, v150, v154
	v_add_f32_e32 v158, v158, v162
	v_add_f32_e32 v150, v150, v158
	v_fmamk_f32 v150, v150, 0x3a800000, v149
	v_rsq_f32_e32 v222, v150
	v_add_f32_e32 v166, v166, v167
	v_add_f32_e32 v168, v168, v169
	v_add_f32_e32 v170, v170, v171
	v_add_f32_e32 v172, v172, v173
	v_add_f32_e32 v174, v174, v175
	v_add_f32_e32 v176, v176, v177
	v_add_f32_e32 v178, v178, v179
	v_add_f32_e32 v180, v180, v181
	v_add_f32_e32 v166, v166, v168
	v_add_f32_e32 v170, v170, v172
	v_add_f32_e32 v174, v174, v176
	v_add_f32_e32 v178, v178, v180
	v_add_f32_e32 v166, v166, v170
	v_add_f32_e32 v174, v174, v178
	v_add_f32_e32 v166, v166, v174
	v_fmamk_f32 v166, v166, 0x3a800000, v149
	v_rsq_f32_e32 v224, v166
	v_add_f32_e32 v186, v186, v187
	v_add_f32_e32 v188, v188, v189
	v_add_f32_e32 v190, v190, v191
	v_add_f32_e32 v192, v192, v193
	v_add_f32_e32 v194, v194, v195
	v_add_f32_e32 v196, v196, v197
	v_add_f32_e32 v198, v198, v199
	v_add_f32_e32 v200, v200, v201
	v_add_f32_e32 v186, v186, v188
	v_add_f32_e32 v190, v190, v192
	v_add_f32_e32 v194, v194, v196
	v_add_f32_e32 v198, v198, v200
	v_add_f32_e32 v186, v186, v190
	v_add_f32_e32 v194, v194, v198
	v_add_f32_e32 v186, v186, v194
	v_fmamk_f32 v186, v186, 0x3a800000, v149
	v_rsq_f32_e32 v226, v186
	v_add_f32_e32 v202, v202, v203
	v_add_f32_e32 v204, v204, v205
	v_add_f32_e32 v206, v206, v207
	v_add_f32_e32 v208, v208, v209
	v_add_f32_e32 v210, v210, v211
	v_add_f32_e32 v212, v212, v213
	v_add_f32_e32 v238, v238, v239
	v_add_f32_e32 v240, v240, v241
	v_add_f32_e32 v202, v202, v204
	v_add_f32_e32 v206, v206, v208
	v_add_f32_e32 v210, v210, v212
	v_add_f32_e32 v238, v238, v240
	v_add_f32_e32 v202, v202, v206
	v_add_f32_e32 v210, v210, v238
	v_add_f32_e32 v202, v202, v210
	v_fmamk_f32 v202, v202, 0x3a800000, v149
	v_rsq_f32_e32 v228, v202
	v_pk_mul_f32 v[48:49], v[48:49], v[222:223] op_sel_hi:[1,0]
	v_pk_mul_f32 v[50:51], v[50:51], v[222:223] op_sel_hi:[1,0]
	v_pk_mul_f32 v[52:53], v[52:53], v[222:223] op_sel_hi:[1,0]
	v_pk_mul_f32 v[54:55], v[54:55], v[222:223] op_sel_hi:[1,0]
	v_pk_mul_f32 v[56:57], v[56:57], v[222:223] op_sel_hi:[1,0]
	v_pk_mul_f32 v[58:59], v[58:59], v[222:223] op_sel_hi:[1,0]
	v_pk_mul_f32 v[60:61], v[60:61], v[222:223] op_sel_hi:[1,0]
	v_pk_mul_f32 v[62:63], v[62:63], v[222:223] op_sel_hi:[1,0]
	v_max_f32_e32 v48, 0, v48
	v_max_f32_e32 v49, 0, v49
	v_max_f32_e32 v50, 0, v50
	v_max_f32_e32 v51, 0, v51
	v_max_f32_e32 v52, 0, v52
	v_max_f32_e32 v53, 0, v53
	v_max_f32_e32 v54, 0, v54
	v_max_f32_e32 v55, 0, v55
	v_max_f32_e32 v56, 0, v56
	v_max_f32_e32 v57, 0, v57
	v_max_f32_e32 v58, 0, v58
	v_max_f32_e32 v59, 0, v59
	v_max_f32_e32 v60, 0, v60
	v_max_f32_e32 v61, 0, v61
	v_max_f32_e32 v62, 0, v62
	v_max_f32_e32 v63, 0, v63
	v_pk_mul_f32 v[48:49], v[48:49], v[48:49]
	v_pk_mul_f32 v[50:51], v[50:51], v[50:51]
	v_pk_mul_f32 v[52:53], v[52:53], v[52:53]
	v_pk_mul_f32 v[54:55], v[54:55], v[54:55]
	v_pk_mul_f32 v[56:57], v[56:57], v[56:57]
	v_pk_mul_f32 v[58:59], v[58:59], v[58:59]
	v_pk_mul_f32 v[60:61], v[60:61], v[60:61]
	v_pk_mul_f32 v[62:63], v[62:63], v[62:63]
	v_cvt_pk_bf16_f32 v230, v60, v61
	v_cvt_pk_bf16_f32 v231, v62, v63
	v_cvt_pk_bf16_f32 v232, v56, v57
	v_cvt_pk_bf16_f32 v233, v58, v59
	v_cvt_pk_bf16_f32 v234, v52, v53
	v_cvt_pk_bf16_f32 v235, v54, v55
	v_cvt_pk_bf16_f32 v236, v48, v49
	v_cvt_pk_bf16_f32 v237, v50, v51
	global_store_dwordx4 v246, v[230:233], s[22:23]
	global_store_dwordx4 v246, v[234:237], s[22:23] offset:256
	s_add_u32 s22, s22, 0x20000
	s_addc_u32 s23, s23, 0
	v_pk_mul_f32 v[32:33], v[32:33], v[224:225] op_sel_hi:[1,0]
	v_pk_mul_f32 v[34:35], v[34:35], v[224:225] op_sel_hi:[1,0]
	v_pk_mul_f32 v[36:37], v[36:37], v[224:225] op_sel_hi:[1,0]
	v_pk_mul_f32 v[38:39], v[38:39], v[224:225] op_sel_hi:[1,0]
	v_pk_mul_f32 v[40:41], v[40:41], v[224:225] op_sel_hi:[1,0]
	v_pk_mul_f32 v[42:43], v[42:43], v[224:225] op_sel_hi:[1,0]
	v_pk_mul_f32 v[44:45], v[44:45], v[224:225] op_sel_hi:[1,0]
	v_pk_mul_f32 v[46:47], v[46:47], v[224:225] op_sel_hi:[1,0]
	v_max_f32_e32 v32, 0, v32
	v_max_f32_e32 v33, 0, v33
	v_max_f32_e32 v34, 0, v34
	v_max_f32_e32 v35, 0, v35
	v_max_f32_e32 v36, 0, v36
; __device__ __forceinline__ u32x4 pack8(f32x4 a, f32x4 b) { u32x4 w; w.x = cvt_pk(a[0], a[1]); w.y = cvt_pk(a[2], a[3]); w.z = cvt_pk(b[0], b[1]); w.w = cvt_pk(b[2], b[3]); return w; }
;     __device__ __forceinline__ void operator()(EPI_ARGS) const {
;     ...
;             for (int m = 0; m < 4; ++m) { const int row = row0 + ai * 128 + m * 16; const float rs = row_rstd(ss, row); bf16_t* rowp = H + (size_t)row * FF + colt;
; #pragma unroll
;                 for (int bj = 0; bj < 2; ++bj) { f32x4 v0 = acc[ai][bj][m][0] * rs, v1 = acc[ai][bj][m][1] * rs;
; #pragma unroll
;                     for (int e = 0; e < 4; ++e) { const float a = fmaxf(v0[e], 0.f), b = fmaxf(v1[e], 0.f); v0[e] = a * a; v1[e] = b * b; }
;                     *(u32x4*)(rowp + bj * 128) = pack8(v0, v1); } }
	v_max_f32_e32 v37, 0, v37
	v_max_f32_e32 v38, 0, v38
	v_max_f32_e32 v39, 0, v39
	v_max_f32_e32 v40, 0, v40
	v_max_f32_e32 v41, 0, v41
	v_max_f32_e32 v42, 0, v42
	v_max_f32_e32 v43, 0, v43
	v_max_f32_e32 v44, 0, v44
	v_max_f32_e32 v45, 0, v45
	v_max_f32_e32 v46, 0, v46
	v_max_f32_e32 v47, 0, v47
	v_pk_mul_f32 v[32:33], v[32:33], v[32:33]
	v_pk_mul_f32 v[34:35], v[34:35], v[34:35]
	v_pk_mul_f32 v[36:37], v[36:37], v[36:37]
	v_pk_mul_f32 v[38:39], v[38:39], v[38:39]
	v_pk_mul_f32 v[40:41], v[40:41], v[40:41]
	v_pk_mul_f32 v[42:43], v[42:43], v[42:43]
	v_pk_mul_f32 v[44:45], v[44:45], v[44:45]
	v_pk_mul_f32 v[46:47], v[46:47], v[46:47]
	v_cvt_pk_bf16_f32 v230, v44, v45
	v_cvt_pk_bf16_f32 v231, v46, v47
	v_cvt_pk_bf16_f32 v232, v40, v41
	v_cvt_pk_bf16_f32 v233, v42, v43
	v_cvt_pk_bf16_f32 v234, v36, v37
	v_cvt_pk_bf16_f32 v235, v38, v39
	v_cvt_pk_bf16_f32 v236, v32, v33
	v_cvt_pk_bf16_f32 v237, v34, v35
	global_store_dwordx4 v246, v[230:233], s[22:23]
	global_store_dwordx4 v246, v[234:237], s[22:23] offset:256
	s_add_u32 s22, s22, 0x20000
	s_addc_u32 s23, s23, 0
	v_pk_mul_f32 v[16:17], v[16:17], v[226:227] op_sel_hi:[1,0]
	v_pk_mul_f32 v[18:19], v[18:19], v[226:227] op_sel_hi:[1,0]
	v_pk_mul_f32 v[20:21], v[20:21], v[226:227] op_sel_hi:[1,0]
	v_pk_mul_f32 v[22:23], v[22:23], v[226:227] op_sel_hi:[1,0]
	v_pk_mul_f32 v[24:25], v[24:25], v[226:227] op_sel_hi:[1,0]
	v_pk_mul_f32 v[26:27], v[26:27], v[226:227] op_sel_hi:[1,0]
	v_pk_mul_f32 v[28:29], v[28:29], v[226:227] op_sel_hi:[1,0]
	v_pk_mul_f32 v[30:31], v[30:31], v[226:227] op_sel_hi:[1,0]
	v_max_f32_e32 v16, 0, v16
	v_max_f32_e32 v17, 0, v17
	v_max_f32_e32 v18, 0, v18
	v_max_f32_e32 v19, 0, v19
	v_max_f32_e32 v20, 0, v20
	v_max_f32_e32 v21, 0, v21
	v_max_f32_e32 v22, 0, v22
	v_max_f32_e32 v23, 0, v23
	v_max_f32_e32 v24, 0, v24
	v_max_f32_e32 v25, 0, v25
	v_max_f32_e32 v26, 0, v26
	v_max_f32_e32 v27, 0, v27
	v_max_f32_e32 v28, 0, v28
	v_max_f32_e32 v29, 0, v29
	v_max_f32_e32 v30, 0, v30
	v_max_f32_e32 v31, 0, v31
	v_pk_mul_f32 v[16:17], v[16:17], v[16:17]
	v_pk_mul_f32 v[18:19], v[18:19], v[18:19]
	v_pk_mul_f32 v[20:21], v[20:21], v[20:21]
	v_pk_mul_f32 v[22:23], v[22:23], v[22:23]
	v_pk_mul_f32 v[24:25], v[24:25], v[24:25]
	v_pk_mul_f32 v[26:27], v[26:27], v[26:27]
	v_pk_mul_f32 v[28:29], v[28:29], v[28:29]
	v_pk_mul_f32 v[30:31], v[30:31], v[30:31]
	v_cvt_pk_bf16_f32 v230, v28, v29
	v_cvt_pk_bf16_f32 v231, v30, v31
	v_cvt_pk_bf16_f32 v232, v24, v25
	v_cvt_pk_bf16_f32 v233, v26, v27
	v_cvt_pk_bf16_f32 v234, v20, v21
	v_cvt_pk_bf16_f32 v235, v22, v23
	v_cvt_pk_bf16_f32 v236, v16, v17
	v_cvt_pk_bf16_f32 v237, v18, v19
	global_store_dwordx4 v246, v[230:233], s[22:23]
	global_store_dwordx4 v246, v[234:237], s[22:23] offset:256
	s_add_u32 s22, s22, 0x20000
	s_addc_u32 s23, s23, 0
	v_pk_mul_f32 v[0:1], v[0:1], v[228:229] op_sel_hi:[1,0]
	v_pk_mul_f32 v[2:3], v[2:3], v[228:229] op_sel_hi:[1,0]
	v_pk_mul_f32 v[4:5], v[4:5], v[228:229] op_sel_hi:[1,0]
	v_pk_mul_f32 v[6:7], v[6:7], v[228:229] op_sel_hi:[1,0]
	v_pk_mul_f32 v[8:9], v[8:9], v[228:229] op_sel_hi:[1,0]
	v_pk_mul_f32 v[10:11], v[10:11], v[228:229] op_sel_hi:[1,0]
	v_pk_mul_f32 v[12:13], v[12:13], v[228:229] op_sel_hi:[1,0]
	v_pk_mul_f32 v[14:15], v[14:15], v[228:229] op_sel_hi:[1,0]
	v_max_f32_e32 v0, 0, v0
	v_max_f32_e32 v1, 0, v1
	v_max_f32_e32 v2, 0, v2
	v_max_f32_e32 v3, 0, v3
	v_max_f32_e32 v4, 0, v4
	v_max_f32_e32 v5, 0, v5
	v_max_f32_e32 v6, 0, v6
	v_max_f32_e32 v7, 0, v7
	v_max_f32_e32 v8, 0, v8
	v_max_f32_e32 v9, 0, v9
	v_max_f32_e32 v10, 0, v10
	v_max_f32_e32 v11, 0, v11
	v_max_f32_e32 v12, 0, v12
	v_max_f32_e32 v13, 0, v13
	v_max_f32_e32 v14, 0, v14
	v_max_f32_e32 v15, 0, v15
	v_pk_mul_f32 v[0:1], v[0:1], v[0:1]
	v_pk_mul_f32 v[2:3], v[2:3], v[2:3]
	v_pk_mul_f32 v[4:5], v[4:5], v[4:5]
	v_pk_mul_f32 v[6:7], v[6:7], v[6:7]
	v_pk_mul_f32 v[8:9], v[8:9], v[8:9]
	v_pk_mul_f32 v[10:11], v[10:11], v[10:11]
	v_pk_mul_f32 v[12:13], v[12:13], v[12:13]
	v_pk_mul_f32 v[14:15], v[14:15], v[14:15]
	v_cvt_pk_bf16_f32 v230, v12, v13
	v_cvt_pk_bf16_f32 v231, v14, v15
	v_cvt_pk_bf16_f32 v232, v8, v9
	v_cvt_pk_bf16_f32 v233, v10, v11
	v_cvt_pk_bf16_f32 v234, v4, v5
	v_cvt_pk_bf16_f32 v235, v6, v7
	v_cvt_pk_bf16_f32 v236, v0, v1
	v_cvt_pk_bf16_f32 v237, v2, v3
	global_store_dwordx4 v246, v[230:233], s[22:23]
	global_store_dwordx4 v246, v[234:237], s[22:23] offset:256
	s_andn2_b64 vcc, exec, s[18:19]
	s_mov_b64 s[18:19], -1
	s_cbranch_vccnz .LBB0_875
	s_andn2_b64 vcc, exec, s[6:7]
	s_cbranch_vccnz .LBB0_874
	s_barrier
	s_branch .LBB0_874
